# planA + gate-up mainloop LDS-DMA issue rebalanced 4/4/4/4 per load interval
# speedup vs baseline: 1.0011x; 1.0011x over previous
; #define PG8_STAGE(bufoff, gbase, voff) do { _Pragma("unroll") for (int _i = 0; _i < 2; ++_i) \
;         __builtin_amdgcn_global_load_lds((const unsigned*)((const char*)(gbase) + (voff)[_i]), (LAS unsigned*)(lds + (bufoff) + ldsw + _i * 8192), 16, 0, 0); } while (0)
; #define PG8_WAIT_V(n) asm volatile("s_waitcnt vmcnt(" #n ")" ::: "memory")
; #define PG8_BAR __builtin_amdgcn_s_barrier()
; template <class Epi, class Sched, bool ALIGN_EPI = false, bool SP2 = false>
; __device__ __forceinline__ void gemm_phase(LAS unsigned char* lds, const Gemm g, const Sched& S, const Epi& E) {
;     ...
;     if constexpr (SP2) {
;         PG8_STAGE(PG8_SB(0, 0), cB, voffB); PG8_STAGE(PG8_SB(0, 1), cB + hstep, voffB); PG8_STAGE(PG8_SA(0, 0), cA, voffA); PG8_STAGE(PG8_SA(0, 1), cA + hstep, voffA);
;         if (wr == 1) PG8_BAR;
;         PG8_WAIT_V(2); PG8_BAR;
;         PG8_STAGE(PG8_SB(1, 0), cB + kstep, voffB); PG8_STAGE(PG8_SA(1, 0), cA + kstep, voffA); PG8_STAGE(PG8_SB(1, 1), cB + hstep + kstep, voffB);
;         PG8_WAIT_V(6); PG8_BAR;
.LBB0_125:
	v_lshrrev_b32_e32 v17, 1, v1
	v_and_b32_e32 v16, 15, v1
	v_and_b32_e32 v17, 24, v17
	v_readlane_b32 s24, v244, 26
	v_lshl_or_b32 v146, s12, 6, v16
	v_lshlrev_b32_e32 v18, 1, v17
	s_lshl_b32 s9, s9, 5
	v_mov_b32_e32 v129, v189
	v_readlane_b32 s25, v244, 27
	v_lshl_or_b32 v16, v16, 6, v18
	v_lshlrev_b32_e32 v18, 2, v146
	s_and_b32 s16, s9, 0x60
	s_add_i32 m0, s38, 0x18000
	v_lshl_add_u64 v[2:3], v[2:3], 0, s[86:87]
	v_lshl_add_u64 v[12:13], s[24:25], 0, v[128:129]
	v_mov_b32_e32 v131, v189
	s_lshl_b32 s12, s12, 13
	v_and_b32_e32 v19, 32, v18
	s_lshl_b32 s9, s16, 7
	s_waitcnt vmcnt(2)
	s_barrier
	global_load_lds_dwordx4 v[2:3], off
	v_lshl_add_u64 v[2:3], v[4:5], 0, s[86:87]
	s_add_i32 m0, s38, 0x1a000
	s_add_i32 s46, s38, 0x8000
	s_add_i32 s47, s38, 0xa000
	v_lshl_add_u64 v[14:15], s[24:25], 0, v[130:131]
	v_bitop3_b32 v19, v16, s12, v19 bitop3:0xde
	global_load_lds_dwordx4 v[2:3], off
	v_mov_b32_e32 v238, v12
	v_mov_b32_e32 v239, v13
	s_add_u32 s12, s26, 0x80080
	v_mov_b32_e32 v240, v14
	v_mov_b32_e32 v241, v15
	s_addc_u32 s13, s27, 0
	s_add_i32 m0, s38, 0x1c000
	v_lshl_add_u64 v[2:3], s[12:13], 0, v[188:189]
	global_load_lds_dwordx4 v[2:3], off
	v_lshl_add_u64 v[2:3], s[12:13], 0, v[132:133]
	s_add_i32 m0, s38, 0x1e000
	v_lshlrev_b32_e32 v1, 2, v1
	global_load_lds_dwordx4 v[2:3], off
	v_and_b32_e32 v1, 32, v1
	v_bitop3_b32 v147, v16, s9, v1 bitop3:0xde
	v_mov_b32_e32 v1, v189
	v_lshl_add_u64 v[134:135], s[10:11], 0, v[0:1]
	v_lshlrev_b32_e32 v0, 15, v6
	v_and_b32_e32 v0, 0xffff0000, v0
	v_lshl_add_u32 v0, v7, 12, v0
	v_and_b32_e32 v1, 1, v6
	v_lshl_or_b32 v0, v1, 6, v0
	v_readlane_b32 s10, v246, 13
	v_lshl_add_u32 v136, v8, 1, v0
	v_lshlrev_b32_e32 v0, 15, v9
	v_add_u32_e32 v149, s10, v18
	v_and_b32_e32 v0, 0xffff0000, v0
	v_readlane_b32 s10, v244, 18
	s_waitcnt vmcnt(4)
	v_lshl_add_u32 v0, v10, 12, v0
	v_and_b32_e32 v1, 1, v9
	v_readlane_b32 s11, v244, 19
	s_cmpk_lt_u32 s8, 0x100
	v_lshl_or_b32 v0, v1, 6, v0
	s_mov_b32 s49, s10
	v_readlane_b32 s10, v244, 22
	s_cselect_b64 s[8:9], -1, 0
	v_or_b32_e32 v148, s16, v17
	v_mov_b32_e32 v137, v189
	v_lshl_add_u32 v138, v11, 1, v0
	v_mov_b32_e32 v139, v189
	s_mov_b32 s51, 0
	v_add_u32_e32 v150, 0, v19
	s_mov_b32 s50, s10
	s_barrier
	v_readlane_b32 s11, v244, 23
	s_branch .LBB0_128

; #define PG8_STAGE(bufoff, gbase, voff) do { _Pragma("unroll") for (int _i = 0; _i < 2; ++_i) \
;         __builtin_amdgcn_global_load_lds((const unsigned*)((const char*)(gbase) + (voff)[_i]), (LAS unsigned*)(lds + (bufoff) + ldsw + _i * 8192), 16, 0, 0); } while (0)
; #define PG8_LDA(dst, b, h) do { _Pragma("unroll") for (int m = 0; m < 4; ++m) _Pragma("unroll") for (int k = 0; k < 2; ++k) dst[m][k] = *(const LAS bf16x8*)(lds + PG8_SA(b, h) + aoff + m * 2048 + k * 1024); } while (0)
; #define PG8_LDB(dst, b, h) do { _Pragma("unroll") for (int n = 0; n < 2; ++n) _Pragma("unroll") for (int k = 0; k < 2; ++k) dst[n][k] = *(const LAS bf16x8*)(lds + PG8_SB(b, h) + boff + n * 2048 + k * 1024); } while (0)
; #define PG8_MMA(ai, bj, At, Bt) do { __builtin_amdgcn_s_setprio(1); _Pragma("unroll") for (int m = 0; m < 4; ++m) _Pragma("unroll") for (int n = 0; n < 2; ++n) _Pragma("unroll") for (int k = 0; k < 2; ++k) \
;         acc[ai][bj][m][n] = __builtin_amdgcn_mfma_f32_16x16x32_bf16(Bt[n][k], At[m][k], acc[ai][bj][m][n], 0, 0, 0); __builtin_amdgcn_s_setprio(0); } while (0)
; #define PG8_WAIT_V(n) asm volatile("s_waitcnt vmcnt(" #n ")" ::: "memory")
; #define PG8_WAIT_L(n) asm volatile("s_waitcnt lgkmcnt(" #n ")" ::: "memory")
; #define PG8_BAR __builtin_amdgcn_s_barrier()
; #define PG8_SCHED __builtin_amdgcn_sched_barrier(0)
; template <class Epi, class Sched, bool ALIGN_EPI = false, bool SP2 = false>
; __device__ __forceinline__ void gemm_phase(LAS unsigned char* lds, const Gemm g, const Sched& S, const Epi& E) {
;     ...
;             PG8_LDB(B0, 0, 0); PG8_LDB(B1, 0, 1); PG8_SCHED; PG8_LDA(At, 0, 0); PG8_STAGE(PG8_SA(1, 1), a1 + hstep, voffA);
;             PG8_WAIT_V(8); PG8_WAIT_L(0); PG8_BAR; PG8_MMA(0, 0, At, B0); PG8_MMA(0, 1, At, B1); PG8_BAR; PG8_SCHED;
;             PG8_LDA(At, 0, 1); PG8_STAGE(PG8_SB(0, 0), b2, voffB); PG8_STAGE(PG8_SB(0, 1), b2 + hstep, voffB); PG8_STAGE(PG8_SA(0, 0), a2, voffA);
.LBB0_134:
	s_add_u32 s26, s24, 0xfff80080
	s_addc_u32 s27, s25, -1
	s_add_i32 s58, 0, 0x10000
	s_cmp_eq_u32 s57, 28
	s_cselect_b32 s29, s52, s27
	s_cselect_b32 s28, s53, s26
	v_add_u32_e32 v144, s58, v147
	s_cselect_b32 s27, s13, s56
	s_cselect_b32 s26, s54, s55
	s_add_i32 s60, 0, 0x14000
	ds_read_b128 v[140:143], v144
	ds_read_b128 v[152:155], v144 offset:1024
	ds_read_b128 v[156:159], v144 offset:2048
	ds_read_b128 v[160:163], v144 offset:3072
	v_add_u32_e32 v144, s60, v147
	ds_read_b128 v[164:167], v144
	ds_read_b128 v[168:171], v144 offset:1024
	ds_read_b128 v[172:175], v144 offset:2048
	ds_read_b128 v[176:179], v144 offset:3072
	v_lshl_add_u64 v[242:243], v[238:239], 0, s[86:87]
	s_mov_b32 m0, s46
	s_nop 0
	global_load_lds_dwordx4 v[242:243], off
	v_lshl_add_u64 v[242:243], v[240:241], 0, s[86:87]
	s_mov_b32 m0, s47
	s_nop 0
	global_load_lds_dwordx4 v[242:243], off
	v_lshl_add_u64 v[144:145], s[24:25], 0, v[136:137]
	s_add_i32 m0, s38, 0xc000
	ds_read_b128 v[180:183], v150
	ds_read_b128 v[202:205], v150 offset:1024
	ds_read_b128 v[206:209], v150 offset:2048
	ds_read_b128 v[210:213], v150 offset:3072
	ds_read_b128 v[222:225], v150 offset:4096
	ds_read_b128 v[226:229], v150 offset:5120
	ds_read_b128 v[230:233], v150 offset:6144
	ds_read_b128 v[234:237], v150 offset:7168
	global_load_lds_dwordx4 v[144:145], off
	v_lshl_add_u64 v[144:145], s[24:25], 0, v[138:139]
	s_add_i32 m0, s38, 0xe000
	s_nop 0
	global_load_lds_dwordx4 v[144:145], off
	s_waitcnt vmcnt(8)
	s_waitcnt lgkmcnt(0)
	s_barrier
	s_setprio 1
	s_waitcnt lgkmcnt(0)
	v_mfma_f32_16x16x32_bf16 v[124:127], v[140:143], v[180:183], v[124:127]
	v_mfma_f32_16x16x32_bf16 v[120:123], v[156:159], v[180:183], v[120:123]
	v_mfma_f32_16x16x32_bf16 v[108:111], v[140:143], v[206:209], v[108:111]
	v_mfma_f32_16x16x32_bf16 v[104:107], v[156:159], v[206:209], v[104:107]
	v_mfma_f32_16x16x32_bf16 v[92:95], v[140:143], v[222:225], v[92:95]
	v_mfma_f32_16x16x32_bf16 v[88:91], v[156:159], v[222:225], v[88:91]
	v_mfma_f32_16x16x32_bf16 v[76:79], v[140:143], v[230:233], v[76:79]
	v_mfma_f32_16x16x32_bf16 v[72:75], v[156:159], v[230:233], v[72:75]
	v_mfma_f32_16x16x32_bf16 v[124:127], v[152:155], v[202:205], v[124:127]
	v_mfma_f32_16x16x32_bf16 v[120:123], v[160:163], v[202:205], v[120:123]
	v_mfma_f32_16x16x32_bf16 v[108:111], v[152:155], v[210:213], v[108:111]
	v_mfma_f32_16x16x32_bf16 v[104:107], v[160:163], v[210:213], v[104:107]
	v_mfma_f32_16x16x32_bf16 v[92:95], v[152:155], v[226:229], v[92:95]
	v_mfma_f32_16x16x32_bf16 v[88:91], v[160:163], v[226:229], v[88:91]
	v_mfma_f32_16x16x32_bf16 v[76:79], v[152:155], v[234:237], v[76:79]
	v_mfma_f32_16x16x32_bf16 v[72:75], v[160:163], v[234:237], v[72:75]
	s_setprio 0
	s_setprio 1
	v_mfma_f32_16x16x32_bf16 v[116:119], v[164:167], v[180:183], v[116:119]
	v_mfma_f32_16x16x32_bf16 v[112:115], v[172:175], v[180:183], v[112:115]
	v_mfma_f32_16x16x32_bf16 v[100:103], v[164:167], v[206:209], v[100:103]
	v_mfma_f32_16x16x32_bf16 v[96:99], v[172:175], v[206:209], v[96:99]
	v_mfma_f32_16x16x32_bf16 v[84:87], v[164:167], v[222:225], v[84:87]
	v_mfma_f32_16x16x32_bf16 v[80:83], v[172:175], v[222:225], v[80:83]
	v_mfma_f32_16x16x32_bf16 v[68:71], v[164:167], v[230:233], v[68:71]
	v_mfma_f32_16x16x32_bf16 v[64:67], v[172:175], v[230:233], v[64:67]
	v_mfma_f32_16x16x32_bf16 v[116:119], v[168:171], v[202:205], v[116:119]
	v_mfma_f32_16x16x32_bf16 v[112:115], v[176:179], v[202:205], v[112:115]
	v_mfma_f32_16x16x32_bf16 v[100:103], v[168:171], v[210:213], v[100:103]
	v_mfma_f32_16x16x32_bf16 v[96:99], v[176:179], v[210:213], v[96:99]
	v_mfma_f32_16x16x32_bf16 v[84:87], v[168:171], v[226:229], v[84:87]
	v_mfma_f32_16x16x32_bf16 v[80:83], v[176:179], v[226:229], v[80:83]
	v_mfma_f32_16x16x32_bf16 v[68:71], v[168:171], v[234:237], v[68:71]
	v_mfma_f32_16x16x32_bf16 v[64:67], v[176:179], v[234:237], v[64:67]
	s_setprio 0
	s_barrier
	s_add_i32 s58, s58, s35
	v_lshl_add_u64 v[144:145], s[26:27], 0, v[188:189]
	s_mov_b32 m0, s58
	ds_read_b128 v[180:183], v150 offset:16384
	ds_read_b128 v[202:205], v150 offset:17408
	ds_read_b128 v[206:209], v150 offset:18432
	ds_read_b128 v[210:213], v150 offset:19456
	ds_read_b128 v[222:225], v150 offset:20480
	ds_read_b128 v[226:229], v150 offset:21504
	ds_read_b128 v[230:233], v150 offset:22528
	ds_read_b128 v[234:237], v150 offset:23552
	global_load_lds_dwordx4 v[144:145], off
	s_add_i32 m0, s58, 0x2000
	s_add_u32 s58, s26, 0x80000
	v_lshl_add_u64 v[214:215], s[26:27], 0, v[132:133]
	s_addc_u32 s59, s27, 0
	s_add_i32 s60, s60, s35
	global_load_lds_dwordx4 v[214:215], off
	v_lshl_add_u64 v[238:239], s[58:59], 0, v[188:189]
	s_mov_b32 m0, s60
	v_lshl_add_u64 v[240:241], s[28:29], 0, v[130:131]
	global_load_lds_dwordx4 v[238:239], off
	v_lshl_add_u64 v[238:239], s[58:59], 0, v[132:133]
	s_add_i32 m0, s60, 0x2000
	s_nop 0
	global_load_lds_dwordx4 v[238:239], off
	v_lshl_add_u64 v[238:239], s[28:29], 0, v[128:129]
	s_waitcnt vmcnt(6)
	s_waitcnt lgkmcnt(0)
	s_barrier
; #define PG8_STAGE(bufoff, gbase, voff) do { _Pragma("unroll") for (int _i = 0; _i < 2; ++_i) \
;         __builtin_amdgcn_global_load_lds((const unsigned*)((const char*)(gbase) + (voff)[_i]), (LAS unsigned*)(lds + (bufoff) + ldsw + _i * 8192), 16, 0, 0); } while (0)
; #define PG8_LDA(dst, b, h) do { _Pragma("unroll") for (int m = 0; m < 4; ++m) _Pragma("unroll") for (int k = 0; k < 2; ++k) dst[m][k] = *(const LAS bf16x8*)(lds + PG8_SA(b, h) + aoff + m * 2048 + k * 1024); } while (0)
; #define PG8_LDB(dst, b, h) do { _Pragma("unroll") for (int n = 0; n < 2; ++n) _Pragma("unroll") for (int k = 0; k < 2; ++k) dst[n][k] = *(const LAS bf16x8*)(lds + PG8_SB(b, h) + boff + n * 2048 + k * 1024); } while (0)
; #define PG8_MMA(ai, bj, At, Bt) do { __builtin_amdgcn_s_setprio(1); _Pragma("unroll") for (int m = 0; m < 4; ++m) _Pragma("unroll") for (int n = 0; n < 2; ++n) _Pragma("unroll") for (int k = 0; k < 2; ++k) \
;         acc[ai][bj][m][n] = __builtin_amdgcn_mfma_f32_16x16x32_bf16(Bt[n][k], At[m][k], acc[ai][bj][m][n], 0, 0, 0); __builtin_amdgcn_s_setprio(0); } while (0)
; #define PG8_WAIT_V(n) asm volatile("s_waitcnt vmcnt(" #n ")" ::: "memory")
; #define PG8_WAIT_L(n) asm volatile("s_waitcnt lgkmcnt(" #n ")" ::: "memory")
; #define PG8_BAR __builtin_amdgcn_s_barrier()
; #define PG8_SCHED __builtin_amdgcn_sched_barrier(0)
; template <class Epi, class Sched, bool ALIGN_EPI = false, bool SP2 = false>
; __device__ __forceinline__ void gemm_phase(LAS unsigned char* lds, const Gemm g, const Sched& S, const Epi& E) {
;     ...
;             PG8_WAIT_V(8); PG8_WAIT_L(0); PG8_BAR; PG8_MMA(1, 0, At, B0); PG8_MMA(1, 1, At, B1); PG8_BAR; PG8_SCHED;
;             PG8_LDB(B0, 1, 0); PG8_LDB(B1, 1, 1); PG8_SCHED; PG8_LDA(At, 1, 0); PG8_STAGE(PG8_SA(0, 1), a2 + hstep, voffA);
	s_setprio 1
	s_waitcnt lgkmcnt(0)
	v_mfma_f32_16x16x32_bf16 v[52:55], v[140:143], v[180:183], v[52:55]
	v_mfma_f32_16x16x32_bf16 v[48:51], v[156:159], v[180:183], v[48:51]
	v_mfma_f32_16x16x32_bf16 v[36:39], v[140:143], v[206:209], v[36:39]
	v_mfma_f32_16x16x32_bf16 v[24:27], v[156:159], v[206:209], v[24:27]
	v_mfma_f32_16x16x32_bf16 v[16:19], v[140:143], v[222:225], v[16:19]
	v_mfma_f32_16x16x32_bf16 v[8:11], v[156:159], v[222:225], v[8:11]
	v_mfma_f32_16x16x32_bf16 v[4:7], v[140:143], v[230:233], v[4:7]
	v_mfma_f32_16x16x32_bf16 v[0:3], v[156:159], v[230:233], v[0:3]
	v_mfma_f32_16x16x32_bf16 v[52:55], v[152:155], v[202:205], v[52:55]
	v_mfma_f32_16x16x32_bf16 v[48:51], v[160:163], v[202:205], v[48:51]
	v_mfma_f32_16x16x32_bf16 v[36:39], v[152:155], v[210:213], v[36:39]
	v_mfma_f32_16x16x32_bf16 v[24:27], v[160:163], v[210:213], v[24:27]
	v_mfma_f32_16x16x32_bf16 v[16:19], v[152:155], v[226:229], v[16:19]
	v_mfma_f32_16x16x32_bf16 v[8:11], v[160:163], v[226:229], v[8:11]
	v_mfma_f32_16x16x32_bf16 v[4:7], v[152:155], v[234:237], v[4:7]
	v_mfma_f32_16x16x32_bf16 v[0:3], v[160:163], v[234:237], v[0:3]
	s_setprio 0
	s_setprio 1
	v_mfma_f32_16x16x32_bf16 v[60:63], v[164:167], v[180:183], v[60:63]
	v_mfma_f32_16x16x32_bf16 v[56:59], v[172:175], v[180:183], v[56:59]
	v_mfma_f32_16x16x32_bf16 v[44:47], v[164:167], v[206:209], v[44:47]
	v_mfma_f32_16x16x32_bf16 v[40:43], v[172:175], v[206:209], v[40:43]
	v_mfma_f32_16x16x32_bf16 v[32:35], v[164:167], v[222:225], v[32:35]
	v_mfma_f32_16x16x32_bf16 v[28:31], v[172:175], v[222:225], v[28:31]
	v_mfma_f32_16x16x32_bf16 v[20:23], v[164:167], v[230:233], v[20:23]
	v_mfma_f32_16x16x32_bf16 v[12:15], v[172:175], v[230:233], v[12:15]
	v_mfma_f32_16x16x32_bf16 v[60:63], v[168:171], v[202:205], v[60:63]
	v_mfma_f32_16x16x32_bf16 v[56:59], v[176:179], v[202:205], v[56:59]
	v_mfma_f32_16x16x32_bf16 v[44:47], v[168:171], v[210:213], v[44:47]
	v_mfma_f32_16x16x32_bf16 v[40:43], v[176:179], v[210:213], v[40:43]
	v_mfma_f32_16x16x32_bf16 v[32:35], v[168:171], v[226:229], v[32:35]
	v_mfma_f32_16x16x32_bf16 v[28:31], v[176:179], v[226:229], v[28:31]
	v_mfma_f32_16x16x32_bf16 v[20:23], v[168:171], v[234:237], v[20:23]
	v_mfma_f32_16x16x32_bf16 v[12:15], v[176:179], v[234:237], v[12:15]
	s_setprio 0
	s_barrier
	s_add_i32 s58, 0, 0x18000
	v_add_u32_e32 v151, s58, v147
	s_add_i32 s59, 0, 0x1c000
	ds_read_b128 v[140:143], v151
	ds_read_b128 v[152:155], v151 offset:1024
	ds_read_b128 v[156:159], v151 offset:2048
	ds_read_b128 v[160:163], v151 offset:3072
	v_add_u32_e32 v151, s59, v147
	ds_read_b128 v[164:167], v151
	ds_read_b128 v[168:171], v151 offset:1024
	ds_read_b128 v[172:175], v151 offset:2048
	ds_read_b128 v[176:179], v151 offset:3072
	s_mov_b32 m0, s38
	s_nop 0
	global_load_lds_dwordx4 v[238:239], off
	s_mov_b32 m0, s39
	s_nop 0
	global_load_lds_dwordx4 v[240:241], off
	s_add_u32 s28, s28, 0x80000
	s_addc_u32 s29, s29, 0
	s_mov_b32 m0, s44
	v_lshl_add_u64 v[242:243], s[28:29], 0, v[128:129]
	ds_read_b128 v[180:183], v150 offset:32768
	ds_read_b128 v[202:205], v150 offset:33792
	ds_read_b128 v[206:209], v150 offset:34816
	ds_read_b128 v[210:213], v150 offset:35840
	ds_read_b128 v[222:225], v150 offset:36864
	ds_read_b128 v[226:229], v150 offset:37888
	ds_read_b128 v[230:233], v150 offset:38912
	ds_read_b128 v[234:237], v150 offset:39936
	global_load_lds_dwordx4 v[242:243], off
	v_lshl_add_u64 v[242:243], s[28:29], 0, v[130:131]
	s_mov_b32 m0, s45
	s_nop 0
	global_load_lds_dwordx4 v[242:243], off
	s_waitcnt vmcnt(8)
	s_waitcnt lgkmcnt(0)
	s_barrier
; #define PG8_STAGE(bufoff, gbase, voff) do { _Pragma("unroll") for (int _i = 0; _i < 2; ++_i) \
;         __builtin_amdgcn_global_load_lds((const unsigned*)((const char*)(gbase) + (voff)[_i]), (LAS unsigned*)(lds + (bufoff) + ldsw + _i * 8192), 16, 0, 0); } while (0)
; #define PG8_LDA(dst, b, h) do { _Pragma("unroll") for (int m = 0; m < 4; ++m) _Pragma("unroll") for (int k = 0; k < 2; ++k) dst[m][k] = *(const LAS bf16x8*)(lds + PG8_SA(b, h) + aoff + m * 2048 + k * 1024); } while (0)
; #define PG8_MMA(ai, bj, At, Bt) do { __builtin_amdgcn_s_setprio(1); _Pragma("unroll") for (int m = 0; m < 4; ++m) _Pragma("unroll") for (int n = 0; n < 2; ++n) _Pragma("unroll") for (int k = 0; k < 2; ++k) \
;         acc[ai][bj][m][n] = __builtin_amdgcn_mfma_f32_16x16x32_bf16(Bt[n][k], At[m][k], acc[ai][bj][m][n], 0, 0, 0); __builtin_amdgcn_s_setprio(0); } while (0)
; #define PG8_WAIT_V(n) asm volatile("s_waitcnt vmcnt(" #n ")" ::: "memory")
; #define PG8_WAIT_L(n) asm volatile("s_waitcnt lgkmcnt(" #n ")" ::: "memory")
; #define PG8_BAR __builtin_amdgcn_s_barrier()
; #define PG8_SCHED __builtin_amdgcn_sched_barrier(0)
; template <class Epi, class Sched, bool ALIGN_EPI = false, bool SP2 = false>
; __device__ __forceinline__ void gemm_phase(LAS unsigned char* lds, const Gemm g, const Sched& S, const Epi& E) {
;     ...
;         for (int t = 0; t < nt; t += 2) {
;     ...
;             PG8_WAIT_V(8); PG8_WAIT_L(0); PG8_BAR; PG8_MMA(0, 0, At, B0); PG8_MMA(0, 1, At, B1); PG8_BAR; PG8_SCHED;
;             PG8_LDA(At, 1, 1); PG8_STAGE(PG8_SB(1, 0), b3, voffB); PG8_STAGE(PG8_SB(1, 1), b3 + hstep, voffB); PG8_STAGE(PG8_SA(1, 0), a3, voffA);
;             PG8_WAIT_V(8); PG8_WAIT_L(0); PG8_BAR; PG8_MMA(1, 0, At, B0); PG8_MMA(1, 1, At, B1); PG8_BAR; PG8_SCHED;
	s_setprio 1
	s_waitcnt lgkmcnt(0)
	v_mfma_f32_16x16x32_bf16 v[124:127], v[140:143], v[180:183], v[124:127]
	v_mfma_f32_16x16x32_bf16 v[120:123], v[156:159], v[180:183], v[120:123]
	v_mfma_f32_16x16x32_bf16 v[108:111], v[140:143], v[206:209], v[108:111]
	v_mfma_f32_16x16x32_bf16 v[104:107], v[156:159], v[206:209], v[104:107]
	v_mfma_f32_16x16x32_bf16 v[92:95], v[140:143], v[222:225], v[92:95]
	v_mfma_f32_16x16x32_bf16 v[88:91], v[156:159], v[222:225], v[88:91]
	v_mfma_f32_16x16x32_bf16 v[76:79], v[140:143], v[230:233], v[76:79]
	v_mfma_f32_16x16x32_bf16 v[72:75], v[156:159], v[230:233], v[72:75]
	v_mfma_f32_16x16x32_bf16 v[124:127], v[152:155], v[202:205], v[124:127]
	v_mfma_f32_16x16x32_bf16 v[120:123], v[160:163], v[202:205], v[120:123]
	v_mfma_f32_16x16x32_bf16 v[108:111], v[152:155], v[210:213], v[108:111]
	v_mfma_f32_16x16x32_bf16 v[104:107], v[160:163], v[210:213], v[104:107]
	v_mfma_f32_16x16x32_bf16 v[92:95], v[152:155], v[226:229], v[92:95]
	v_mfma_f32_16x16x32_bf16 v[88:91], v[160:163], v[226:229], v[88:91]
	v_mfma_f32_16x16x32_bf16 v[76:79], v[152:155], v[234:237], v[76:79]
	v_mfma_f32_16x16x32_bf16 v[72:75], v[160:163], v[234:237], v[72:75]
	s_setprio 0
	s_setprio 1
	v_mfma_f32_16x16x32_bf16 v[116:119], v[164:167], v[180:183], v[116:119]
	v_mfma_f32_16x16x32_bf16 v[112:115], v[172:175], v[180:183], v[112:115]
	v_mfma_f32_16x16x32_bf16 v[100:103], v[164:167], v[206:209], v[100:103]
	v_mfma_f32_16x16x32_bf16 v[96:99], v[172:175], v[206:209], v[96:99]
	v_mfma_f32_16x16x32_bf16 v[84:87], v[164:167], v[222:225], v[84:87]
	v_mfma_f32_16x16x32_bf16 v[80:83], v[172:175], v[222:225], v[80:83]
	v_mfma_f32_16x16x32_bf16 v[68:71], v[164:167], v[230:233], v[68:71]
	v_mfma_f32_16x16x32_bf16 v[64:67], v[172:175], v[230:233], v[64:67]
	v_mfma_f32_16x16x32_bf16 v[116:119], v[168:171], v[202:205], v[116:119]
	v_mfma_f32_16x16x32_bf16 v[112:115], v[176:179], v[202:205], v[112:115]
	v_mfma_f32_16x16x32_bf16 v[100:103], v[168:171], v[210:213], v[100:103]
	v_mfma_f32_16x16x32_bf16 v[96:99], v[176:179], v[210:213], v[96:99]
	v_mfma_f32_16x16x32_bf16 v[84:87], v[168:171], v[226:229], v[84:87]
	v_mfma_f32_16x16x32_bf16 v[80:83], v[176:179], v[226:229], v[80:83]
	v_mfma_f32_16x16x32_bf16 v[68:71], v[168:171], v[234:237], v[68:71]
	v_mfma_f32_16x16x32_bf16 v[64:67], v[176:179], v[234:237], v[64:67]
	s_setprio 0
	s_barrier
	s_add_i32 s28, s58, s35
	v_lshl_add_u64 v[144:145], v[144:145], 0, s[86:87]
	s_mov_b32 m0, s28
	ds_read_b128 v[180:183], v150 offset:49152
	ds_read_b128 v[202:205], v150 offset:50176
	ds_read_b128 v[206:209], v150 offset:51200
	ds_read_b128 v[210:213], v150 offset:52224
	ds_read_b128 v[222:225], v150 offset:53248
	ds_read_b128 v[226:229], v150 offset:54272
	ds_read_b128 v[230:233], v150 offset:55296
	ds_read_b128 v[234:237], v150 offset:56320
	global_load_lds_dwordx4 v[144:145], off
	s_add_i32 m0, s28, 0x2000
	s_add_u32 s26, s26, 0x80080
	v_lshl_add_u64 v[144:145], v[214:215], 0, s[86:87]
	s_addc_u32 s27, s27, 0
	s_add_i32 s28, s59, s35
	global_load_lds_dwordx4 v[144:145], off
	v_lshl_add_u64 v[144:145], s[26:27], 0, v[188:189]
	s_mov_b32 m0, s28
	s_nop 0
	global_load_lds_dwordx4 v[144:145], off
	v_lshl_add_u64 v[144:145], s[26:27], 0, v[132:133]
	s_add_i32 m0, s28, 0x2000
	s_nop 0
	global_load_lds_dwordx4 v[144:145], off
	s_waitcnt vmcnt(6)
	s_waitcnt lgkmcnt(0)
	s_barrier
	s_setprio 1
	s_waitcnt lgkmcnt(0)
	v_mfma_f32_16x16x32_bf16 v[52:55], v[140:143], v[180:183], v[52:55]
	v_mfma_f32_16x16x32_bf16 v[48:51], v[156:159], v[180:183], v[48:51]
	v_mfma_f32_16x16x32_bf16 v[36:39], v[140:143], v[206:209], v[36:39]
	v_mfma_f32_16x16x32_bf16 v[24:27], v[156:159], v[206:209], v[24:27]
	v_mfma_f32_16x16x32_bf16 v[16:19], v[140:143], v[222:225], v[16:19]
	v_mfma_f32_16x16x32_bf16 v[8:11], v[156:159], v[222:225], v[8:11]
	v_mfma_f32_16x16x32_bf16 v[4:7], v[140:143], v[230:233], v[4:7]
	v_mfma_f32_16x16x32_bf16 v[0:3], v[156:159], v[230:233], v[0:3]
	v_mfma_f32_16x16x32_bf16 v[52:55], v[152:155], v[202:205], v[52:55]
	v_mfma_f32_16x16x32_bf16 v[48:51], v[160:163], v[202:205], v[48:51]
	v_mfma_f32_16x16x32_bf16 v[36:39], v[152:155], v[210:213], v[36:39]
	v_mfma_f32_16x16x32_bf16 v[24:27], v[160:163], v[210:213], v[24:27]
	v_mfma_f32_16x16x32_bf16 v[16:19], v[152:155], v[226:229], v[16:19]
	v_mfma_f32_16x16x32_bf16 v[8:11], v[160:163], v[226:229], v[8:11]
	v_mfma_f32_16x16x32_bf16 v[4:7], v[152:155], v[234:237], v[4:7]
	v_mfma_f32_16x16x32_bf16 v[0:3], v[160:163], v[234:237], v[0:3]
	s_setprio 0
	s_setprio 1
	v_mfma_f32_16x16x32_bf16 v[60:63], v[164:167], v[180:183], v[60:63]
	v_mfma_f32_16x16x32_bf16 v[56:59], v[172:175], v[180:183], v[56:59]
	v_mfma_f32_16x16x32_bf16 v[44:47], v[164:167], v[206:209], v[44:47]
	v_mfma_f32_16x16x32_bf16 v[40:43], v[172:175], v[206:209], v[40:43]
	v_mfma_f32_16x16x32_bf16 v[32:35], v[164:167], v[222:225], v[32:35]
	v_mfma_f32_16x16x32_bf16 v[28:31], v[172:175], v[222:225], v[28:31]
	v_mfma_f32_16x16x32_bf16 v[20:23], v[164:167], v[230:233], v[20:23]
	v_mfma_f32_16x16x32_bf16 v[12:15], v[172:175], v[230:233], v[12:15]
	v_mfma_f32_16x16x32_bf16 v[60:63], v[168:171], v[202:205], v[60:63]
	v_mfma_f32_16x16x32_bf16 v[56:59], v[176:179], v[202:205], v[56:59]
	v_mfma_f32_16x16x32_bf16 v[44:47], v[168:171], v[210:213], v[44:47]
	v_mfma_f32_16x16x32_bf16 v[40:43], v[176:179], v[210:213], v[40:43]
	v_mfma_f32_16x16x32_bf16 v[32:35], v[168:171], v[226:229], v[32:35]
	v_mfma_f32_16x16x32_bf16 v[28:31], v[176:179], v[226:229], v[28:31]
	v_mfma_f32_16x16x32_bf16 v[20:23], v[168:171], v[234:237], v[20:23]
	v_mfma_f32_16x16x32_bf16 v[12:15], v[176:179], v[234:237], v[12:15]
	s_setprio 0
	s_barrier
	s_add_i32 s57, s57, 2
	s_add_u32 s24, s24, 0x100
	s_addc_u32 s25, s25, 0
	s_add_u32 s55, s55, 0x100
	s_addc_u32 s56, s56, 0
	s_cmp_gt_u32 s57, 29
	s_cbranch_scc0 .LBB0_134
	s_and_b64 vcc, exec, s[8:9]
	s_cbranch_vccz .LBB0_137
	s_barrier
